# GEMM tile start: accumulators cleared with 64 v_mov_b64 instead of 128 v_mov_b32 (on top of the P7 load hoist)
# speedup vs baseline: 1.0000x; 1.0000x over previous
.LBB0_258:
	s_ashr_i32 s15, s14, 31
	s_lshl_b64 s[16:17], s[14:15], 19
	s_add_u32 s16, s28, s16
	s_addc_u32 s17, s29, s17
	s_and_b64 s[18:19], s[0:1], exec
	s_cselect_b32 s15, s17, s23
	s_cselect_b32 s47, s16, s22
	s_ashr_i32 s13, s12, 31
	s_lshl_b64 s[18:19], s[12:13], 19
	s_add_u32 s18, s30, s18
	s_addc_u32 s19, s31, s19
	s_and_b64 s[26:27], s[0:1], exec
	s_cselect_b32 s13, s19, s25
	s_cselect_b32 s48, s18, s24
	s_add_u32 s22, s22, 0x40080
	s_addc_u32 s23, s23, 0
	s_add_u32 s49, s24, 0x100
	v_mov_b32_e32 v0, 0
	s_addc_u32 s50, s25, 0
	s_mov_b32 s51, -2
	v_mov_b32_e32 v1, v0
	v_mov_b64_e32 v[2:3], 0
	v_mov_b64_e32 v[4:5], 0
	v_mov_b64_e32 v[6:7], 0
	v_mov_b64_e32 v[16:17], 0
	v_mov_b64_e32 v[18:19], 0
	v_mov_b64_e32 v[20:21], 0
	v_mov_b64_e32 v[22:23], 0
	v_mov_b64_e32 v[32:33], 0
	v_mov_b64_e32 v[34:35], 0
	v_mov_b64_e32 v[36:37], 0
	v_mov_b64_e32 v[38:39], 0
	v_mov_b64_e32 v[48:49], 0
	v_mov_b64_e32 v[50:51], 0
	v_mov_b64_e32 v[52:53], 0
	v_mov_b64_e32 v[54:55], 0
	v_mov_b64_e32 v[8:9], 0
	v_mov_b64_e32 v[10:11], 0
	v_mov_b64_e32 v[12:13], 0
	v_mov_b64_e32 v[14:15], 0
	v_mov_b64_e32 v[24:25], 0
	v_mov_b64_e32 v[26:27], 0
	v_mov_b64_e32 v[28:29], 0
	v_mov_b64_e32 v[30:31], 0
	v_mov_b64_e32 v[40:41], 0
	v_mov_b64_e32 v[42:43], 0
	v_mov_b64_e32 v[44:45], 0
	v_mov_b64_e32 v[46:47], 0
	v_mov_b64_e32 v[56:57], 0
	v_mov_b64_e32 v[58:59], 0
	v_mov_b64_e32 v[60:61], 0
	v_mov_b64_e32 v[62:63], 0
	v_mov_b64_e32 v[64:65], 0
	v_mov_b64_e32 v[66:67], 0
	v_mov_b64_e32 v[68:69], 0
	v_mov_b64_e32 v[70:71], 0
	v_mov_b64_e32 v[80:81], 0
	v_mov_b64_e32 v[82:83], 0
	v_mov_b64_e32 v[84:85], 0
	v_mov_b64_e32 v[86:87], 0
	v_mov_b64_e32 v[96:97], 0
	v_mov_b64_e32 v[98:99], 0
	v_mov_b64_e32 v[100:101], 0
	v_mov_b64_e32 v[102:103], 0
	v_mov_b64_e32 v[112:113], 0
	v_mov_b64_e32 v[114:115], 0
	v_mov_b64_e32 v[116:117], 0
	v_mov_b64_e32 v[118:119], 0
	v_mov_b64_e32 v[72:73], 0
	v_mov_b64_e32 v[74:75], 0
	v_mov_b64_e32 v[76:77], 0
	v_mov_b64_e32 v[78:79], 0
	v_mov_b64_e32 v[88:89], 0
	v_mov_b64_e32 v[90:91], 0
	v_mov_b64_e32 v[92:93], 0
	v_mov_b64_e32 v[94:95], 0
	v_mov_b64_e32 v[104:105], 0
	v_mov_b64_e32 v[106:107], 0
	v_mov_b64_e32 v[108:109], 0
	v_mov_b64_e32 v[110:111], 0
	v_mov_b64_e32 v[120:121], 0
	v_mov_b64_e32 v[122:123], 0
	v_mov_b64_e32 v[124:125], 0
	v_mov_b64_e32 v[126:127], 0

.LBB0_337:
	s_add_u32 s24, s24, 0xb0080
	s_addc_u32 s25, s25, 0
	s_add_u32 s55, s26, 0x100
	v_mov_b32_e32 v0, 0
	s_addc_u32 s56, s27, 0
	s_mov_b32 s57, -2
	v_mov_b32_e32 v1, v0
	v_mov_b64_e32 v[2:3], 0
	v_mov_b64_e32 v[4:5], 0
	v_mov_b64_e32 v[6:7], 0
	v_mov_b64_e32 v[8:9], 0
	v_mov_b64_e32 v[10:11], 0
	v_mov_b64_e32 v[12:13], 0
	v_mov_b64_e32 v[14:15], 0
	v_mov_b64_e32 v[24:25], 0
	v_mov_b64_e32 v[26:27], 0
	v_mov_b64_e32 v[28:29], 0
	v_mov_b64_e32 v[30:31], 0
	v_mov_b64_e32 v[40:41], 0
	v_mov_b64_e32 v[42:43], 0
	v_mov_b64_e32 v[44:45], 0
	v_mov_b64_e32 v[46:47], 0
	v_mov_b64_e32 v[16:17], 0
	v_mov_b64_e32 v[18:19], 0
	v_mov_b64_e32 v[20:21], 0
	v_mov_b64_e32 v[22:23], 0
	v_mov_b64_e32 v[32:33], 0
	v_mov_b64_e32 v[34:35], 0
	v_mov_b64_e32 v[36:37], 0
	v_mov_b64_e32 v[38:39], 0
	v_mov_b64_e32 v[48:49], 0
	v_mov_b64_e32 v[50:51], 0
	v_mov_b64_e32 v[52:53], 0
	v_mov_b64_e32 v[54:55], 0
	v_mov_b64_e32 v[56:57], 0
	v_mov_b64_e32 v[58:59], 0
	v_mov_b64_e32 v[60:61], 0
	v_mov_b64_e32 v[62:63], 0
	v_mov_b64_e32 v[64:65], 0
	v_mov_b64_e32 v[66:67], 0
	v_mov_b64_e32 v[68:69], 0
	v_mov_b64_e32 v[70:71], 0
	v_mov_b64_e32 v[72:73], 0
	v_mov_b64_e32 v[74:75], 0
	v_mov_b64_e32 v[76:77], 0
	v_mov_b64_e32 v[78:79], 0
	v_mov_b64_e32 v[88:89], 0
	v_mov_b64_e32 v[90:91], 0
	v_mov_b64_e32 v[92:93], 0
	v_mov_b64_e32 v[94:95], 0
	v_mov_b64_e32 v[104:105], 0
	v_mov_b64_e32 v[106:107], 0
	v_mov_b64_e32 v[108:109], 0
	v_mov_b64_e32 v[110:111], 0
	v_mov_b64_e32 v[80:81], 0
	v_mov_b64_e32 v[82:83], 0
	v_mov_b64_e32 v[84:85], 0
	v_mov_b64_e32 v[86:87], 0
	v_mov_b64_e32 v[96:97], 0
	v_mov_b64_e32 v[98:99], 0
	v_mov_b64_e32 v[100:101], 0
	v_mov_b64_e32 v[102:103], 0
	v_mov_b64_e32 v[112:113], 0
	v_mov_b64_e32 v[114:115], 0
	v_mov_b64_e32 v[116:117], 0
	v_mov_b64_e32 v[118:119], 0
	v_mov_b64_e32 v[120:121], 0
	v_mov_b64_e32 v[122:123], 0
	v_mov_b64_e32 v[124:125], 0
	v_mov_b64_e32 v[126:127], 0

.LBB0_474:
	s_ashr_i32 s39, s38, 31
	s_lshl_b64 s[40:41], s[38:39], 19
	s_add_u32 s40, s52, s40
	s_addc_u32 s41, s53, s41
	s_and_b64 s[42:43], s[6:7], exec
	s_cselect_b32 s1, s41, s47
	s_cselect_b32 s39, s40, s46
	s_ashr_i32 s37, s36, 31
	s_lshl_b64 s[42:43], s[36:37], 19
	s_add_u32 s42, s54, s42
	s_addc_u32 s43, s55, s43
	s_and_b64 s[50:51], s[6:7], exec
	s_cselect_b32 s37, s43, s49
	s_cselect_b32 s45, s42, s48
	s_add_u32 s46, s46, 0x40080
	s_addc_u32 s47, s47, 0
	s_add_u32 s75, s48, 0x100
	v_mov_b32_e32 v48, 0
	s_addc_u32 s76, s49, 0
	s_mov_b32 s77, -2
	v_mov_b32_e32 v49, v48
	v_mov_b64_e32 v[50:51], 0
	v_mov_b64_e32 v[68:69], 0
	v_mov_b64_e32 v[70:71], 0
	v_mov_b64_e32 v[72:73], 0
	v_mov_b64_e32 v[74:75], 0
	v_mov_b64_e32 v[76:77], 0
	v_mov_b64_e32 v[78:79], 0
	v_mov_b64_e32 v[80:81], 0
	v_mov_b64_e32 v[82:83], 0
	v_mov_b64_e32 v[84:85], 0
	v_mov_b64_e32 v[86:87], 0
	v_mov_b64_e32 v[88:89], 0
	v_mov_b64_e32 v[90:91], 0
	v_mov_b64_e32 v[92:93], 0
	v_mov_b64_e32 v[94:95], 0
	v_mov_b64_e32 v[0:1], 0
	v_mov_b64_e32 v[2:3], 0
	v_mov_b64_e32 v[32:33], 0
	v_mov_b64_e32 v[34:35], 0
	v_mov_b64_e32 v[4:5], 0
	v_mov_b64_e32 v[6:7], 0
	v_mov_b64_e32 v[36:37], 0
	v_mov_b64_e32 v[38:39], 0
	v_mov_b64_e32 v[8:9], 0
	v_mov_b64_e32 v[10:11], 0
	v_mov_b64_e32 v[40:41], 0
	v_mov_b64_e32 v[42:43], 0
	v_mov_b64_e32 v[12:13], 0
	v_mov_b64_e32 v[14:15], 0
	v_mov_b64_e32 v[44:45], 0
	v_mov_b64_e32 v[46:47], 0
	v_mov_b64_e32 v[96:97], 0
	v_mov_b64_e32 v[98:99], 0
	v_mov_b64_e32 v[100:101], 0
	v_mov_b64_e32 v[102:103], 0
	v_mov_b64_e32 v[104:105], 0
	v_mov_b64_e32 v[106:107], 0
	v_mov_b64_e32 v[108:109], 0
	v_mov_b64_e32 v[110:111], 0
	v_mov_b64_e32 v[112:113], 0
	v_mov_b64_e32 v[114:115], 0
	v_mov_b64_e32 v[116:117], 0
	v_mov_b64_e32 v[118:119], 0
	v_mov_b64_e32 v[120:121], 0
	v_mov_b64_e32 v[122:123], 0
	v_mov_b64_e32 v[124:125], 0
	v_mov_b64_e32 v[126:127], 0
	v_mov_b64_e32 v[16:17], 0
	v_mov_b64_e32 v[18:19], 0
	v_mov_b64_e32 v[52:53], 0
	v_mov_b64_e32 v[54:55], 0
	v_mov_b64_e32 v[20:21], 0
	v_mov_b64_e32 v[22:23], 0
	v_mov_b64_e32 v[56:57], 0
	v_mov_b64_e32 v[58:59], 0
	v_mov_b64_e32 v[24:25], 0
	v_mov_b64_e32 v[26:27], 0
	v_mov_b64_e32 v[60:61], 0
	v_mov_b64_e32 v[62:63], 0
	v_mov_b64_e32 v[28:29], 0
	v_mov_b64_e32 v[30:31], 0
	v_mov_b64_e32 v[64:65], 0
	v_mov_b64_e32 v[66:67], 0

.LBB0_1273:
	s_ashr_i32 s23, s22, 31
	s_lshl_b64 s[26:27], s[22:23], 20
	s_add_u32 s26, s35, s26
	s_addc_u32 s27, s36, s27
	s_and_b64 s[4:5], s[4:5], exec
	s_cselect_b32 s23, s27, s29
	s_cselect_b32 s56, s26, s28
	s_add_u32 s4, s30, 0x160080
	s_addc_u32 s5, s31, 0
	s_add_u32 s57, s28, 0x100
	v_mov_b32_e32 v0, 0
	s_addc_u32 s58, s29, 0
	s_mov_b32 s59, -2
	v_mov_b32_e32 v1, v0
	v_mov_b64_e32 v[2:3], 0
	v_mov_b64_e32 v[4:5], 0
	v_mov_b64_e32 v[6:7], 0
	v_mov_b64_e32 v[8:9], 0
	v_mov_b64_e32 v[10:11], 0
	v_mov_b64_e32 v[12:13], 0
	v_mov_b64_e32 v[14:15], 0
	v_mov_b64_e32 v[24:25], 0
	v_mov_b64_e32 v[26:27], 0
	v_mov_b64_e32 v[28:29], 0
	v_mov_b32_e32 v30, v0
	s_waitcnt lgkmcnt(0)
	v_mov_b32_e32 v31, v0
	v_mov_b64_e32 v[40:41], 0
	v_mov_b64_e32 v[42:43], 0
	v_mov_b64_e32 v[44:45], 0
	v_mov_b64_e32 v[46:47], 0
	v_mov_b64_e32 v[16:17], 0
	v_mov_b64_e32 v[18:19], 0
	v_mov_b64_e32 v[20:21], 0
	v_mov_b64_e32 v[22:23], 0
	v_mov_b64_e32 v[32:33], 0
	v_mov_b64_e32 v[34:35], 0
	v_mov_b64_e32 v[36:37], 0
	v_mov_b64_e32 v[38:39], 0
	v_mov_b64_e32 v[48:49], 0
	v_mov_b64_e32 v[50:51], 0
	v_mov_b64_e32 v[52:53], 0
	v_mov_b64_e32 v[54:55], 0
	v_mov_b64_e32 v[56:57], 0
	v_mov_b64_e32 v[58:59], 0
	v_mov_b64_e32 v[60:61], 0
	v_mov_b64_e32 v[62:63], 0
	v_mov_b64_e32 v[64:65], 0
	v_mov_b64_e32 v[66:67], 0
	v_mov_b64_e32 v[68:69], 0
	v_mov_b64_e32 v[70:71], 0
	v_mov_b64_e32 v[72:73], 0
	v_mov_b64_e32 v[74:75], 0
	v_mov_b64_e32 v[76:77], 0
	v_mov_b64_e32 v[78:79], 0
	v_mov_b64_e32 v[88:89], 0
	v_mov_b64_e32 v[90:91], 0
	v_mov_b64_e32 v[92:93], 0
	v_mov_b64_e32 v[94:95], 0
	v_mov_b64_e32 v[104:105], 0
	v_mov_b64_e32 v[106:107], 0
	v_mov_b64_e32 v[108:109], 0
	v_mov_b64_e32 v[110:111], 0
	v_mov_b64_e32 v[80:81], 0
	v_mov_b64_e32 v[82:83], 0
	v_mov_b64_e32 v[84:85], 0
	v_mov_b64_e32 v[86:87], 0
	v_mov_b64_e32 v[96:97], 0
	v_mov_b64_e32 v[98:99], 0
	v_mov_b64_e32 v[100:101], 0
	v_mov_b64_e32 v[102:103], 0
	v_mov_b64_e32 v[112:113], 0
	v_mov_b64_e32 v[114:115], 0
	v_mov_b64_e32 v[116:117], 0
	v_mov_b64_e32 v[118:119], 0
	v_mov_b64_e32 v[120:121], 0
	v_mov_b64_e32 v[122:123], 0
	v_mov_b64_e32 v[124:125], 0
	v_mov_b64_e32 v[126:127], 0

.LBB0_1408:
	s_ashr_i32 s15, s14, 31
	s_lshl_b64 s[16:17], s[14:15], 19
	s_add_u32 s16, s28, s16
	s_addc_u32 s17, s29, s17
	s_and_b64 s[18:19], s[0:1], exec
	s_cselect_b32 s15, s17, s23
	s_cselect_b32 s47, s16, s22
	s_ashr_i32 s13, s12, 31
	s_lshl_b64 s[18:19], s[12:13], 19
	s_add_u32 s18, s30, s18
	s_addc_u32 s19, s31, s19
	s_and_b64 s[26:27], s[0:1], exec
	s_cselect_b32 s13, s19, s25
	s_cselect_b32 s48, s18, s24
	s_add_u32 s22, s22, 0x40080
	s_addc_u32 s23, s23, 0
	s_add_u32 s49, s24, 0x100
	v_mov_b32_e32 v0, 0
	s_addc_u32 s50, s25, 0
	s_mov_b32 s51, -2
	v_mov_b32_e32 v1, v0
	v_mov_b64_e32 v[2:3], 0
	v_mov_b64_e32 v[4:5], 0
	v_mov_b64_e32 v[6:7], 0
	v_mov_b64_e32 v[16:17], 0
	v_mov_b64_e32 v[18:19], 0
	v_mov_b64_e32 v[20:21], 0
	v_mov_b64_e32 v[22:23], 0
	v_mov_b64_e32 v[32:33], 0
	v_mov_b32_e32 v34, v0
	s_waitcnt lgkmcnt(0)
	v_mov_b32_e32 v35, v0
	v_mov_b64_e32 v[36:37], 0
	v_mov_b64_e32 v[38:39], 0
	v_mov_b64_e32 v[48:49], 0
	v_mov_b64_e32 v[50:51], 0
	v_mov_b64_e32 v[52:53], 0
	v_mov_b64_e32 v[54:55], 0
	v_mov_b64_e32 v[8:9], 0
	v_mov_b64_e32 v[10:11], 0
	v_mov_b64_e32 v[12:13], 0
	v_mov_b64_e32 v[14:15], 0
	v_mov_b64_e32 v[24:25], 0
	v_mov_b64_e32 v[26:27], 0
	v_mov_b64_e32 v[28:29], 0
	v_mov_b64_e32 v[30:31], 0
	v_mov_b64_e32 v[40:41], 0
	v_mov_b64_e32 v[42:43], 0
	v_mov_b64_e32 v[44:45], 0
	v_mov_b64_e32 v[46:47], 0
	v_mov_b64_e32 v[56:57], 0
	v_mov_b64_e32 v[58:59], 0
	v_mov_b64_e32 v[60:61], 0
	v_mov_b64_e32 v[62:63], 0
	v_mov_b64_e32 v[64:65], 0
	v_mov_b64_e32 v[66:67], 0
	v_mov_b64_e32 v[68:69], 0
	v_mov_b64_e32 v[70:71], 0
	v_mov_b64_e32 v[80:81], 0
	v_mov_b64_e32 v[82:83], 0
	v_mov_b64_e32 v[84:85], 0
	v_mov_b64_e32 v[86:87], 0
	v_mov_b64_e32 v[96:97], 0
	v_mov_b64_e32 v[98:99], 0
	v_mov_b64_e32 v[100:101], 0
	v_mov_b64_e32 v[102:103], 0
	v_mov_b64_e32 v[112:113], 0
	v_mov_b64_e32 v[114:115], 0
	v_mov_b64_e32 v[116:117], 0
	v_mov_b64_e32 v[118:119], 0
	v_mov_b64_e32 v[72:73], 0
	v_mov_b64_e32 v[74:75], 0
	v_mov_b64_e32 v[76:77], 0
	v_mov_b64_e32 v[78:79], 0
	v_mov_b64_e32 v[88:89], 0
	v_mov_b64_e32 v[90:91], 0
	v_mov_b64_e32 v[92:93], 0
	v_mov_b64_e32 v[94:95], 0
	v_mov_b64_e32 v[104:105], 0
	v_mov_b64_e32 v[106:107], 0
	v_mov_b64_e32 v[108:109], 0
	v_mov_b64_e32 v[110:111], 0
	v_mov_b64_e32 v[120:121], 0
	v_mov_b64_e32 v[122:123], 0
	v_mov_b64_e32 v[124:125], 0
	v_mov_b64_e32 v[126:127], 0

.LBB0_1487:
	s_add_u32 s24, s24, 0xb0080
	s_addc_u32 s25, s25, 0
	s_add_u32 s55, s26, 0x100
	v_mov_b32_e32 v0, 0
	s_addc_u32 s56, s27, 0
	s_mov_b32 s57, -2
	v_mov_b32_e32 v1, v0
	v_mov_b64_e32 v[2:3], 0
	v_mov_b64_e32 v[4:5], 0
	v_mov_b64_e32 v[6:7], 0
	v_mov_b64_e32 v[8:9], 0
	v_mov_b64_e32 v[10:11], 0
	v_mov_b64_e32 v[12:13], 0
	v_mov_b64_e32 v[14:15], 0
	v_mov_b64_e32 v[24:25], 0
	v_mov_b64_e32 v[26:27], 0
	v_mov_b64_e32 v[28:29], 0
	v_mov_b32_e32 v30, v0
	s_waitcnt lgkmcnt(0)
	v_mov_b32_e32 v31, v0
	v_mov_b64_e32 v[40:41], 0
	v_mov_b64_e32 v[42:43], 0
	v_mov_b64_e32 v[44:45], 0
	v_mov_b64_e32 v[46:47], 0
	v_mov_b64_e32 v[16:17], 0
	v_mov_b64_e32 v[18:19], 0
	v_mov_b64_e32 v[20:21], 0
	v_mov_b64_e32 v[22:23], 0
	v_mov_b64_e32 v[32:33], 0
	v_mov_b64_e32 v[34:35], 0
	v_mov_b64_e32 v[36:37], 0
	v_mov_b64_e32 v[38:39], 0
	v_mov_b64_e32 v[48:49], 0
	v_mov_b64_e32 v[50:51], 0
	v_mov_b64_e32 v[52:53], 0
	v_mov_b64_e32 v[54:55], 0
	v_mov_b64_e32 v[56:57], 0
	v_mov_b64_e32 v[58:59], 0
	v_mov_b64_e32 v[60:61], 0
	v_mov_b64_e32 v[62:63], 0
	v_mov_b64_e32 v[64:65], 0
	v_mov_b64_e32 v[66:67], 0
	v_mov_b64_e32 v[68:69], 0
	v_mov_b64_e32 v[70:71], 0
	v_mov_b64_e32 v[72:73], 0
	v_mov_b64_e32 v[74:75], 0
	v_mov_b64_e32 v[76:77], 0
	v_mov_b64_e32 v[78:79], 0
	v_mov_b64_e32 v[88:89], 0
	v_mov_b64_e32 v[90:91], 0
	v_mov_b64_e32 v[92:93], 0
	v_mov_b64_e32 v[94:95], 0
	v_mov_b64_e32 v[104:105], 0
	v_mov_b64_e32 v[106:107], 0
	v_mov_b64_e32 v[108:109], 0
	v_mov_b64_e32 v[110:111], 0
	v_mov_b64_e32 v[80:81], 0
	v_mov_b64_e32 v[82:83], 0
	v_mov_b64_e32 v[84:85], 0
	v_mov_b64_e32 v[86:87], 0
	v_mov_b64_e32 v[96:97], 0
	v_mov_b64_e32 v[98:99], 0
	v_mov_b64_e32 v[100:101], 0
	v_mov_b64_e32 v[102:103], 0
	v_mov_b64_e32 v[112:113], 0
	v_mov_b64_e32 v[114:115], 0
	v_mov_b64_e32 v[116:117], 0
	v_mov_b64_e32 v[118:119], 0
	v_mov_b64_e32 v[120:121], 0
	v_mov_b64_e32 v[122:123], 0
	v_mov_b64_e32 v[124:125], 0
	v_mov_b64_e32 v[126:127], 0
